# v5 + P0 small weight transposes: 16 row loads per tile issued back to back (one wait) instead of 16 dependent round trips
# speedup vs baseline: 1.0075x; 1.0075x over previous
.LBB0_27:
	s_cmpk_gt_i32 s47, 0x5f
	s_mov_b64 s[0:1], -1
	s_cbranch_scc0 .LBB0_141
	s_cmpk_gt_u32 s47, 0xd7
	s_cbranch_scc0 .LBB0_38
	s_cmpk_gt_u32 s47, 0xe7
	s_cbranch_scc0 .LBB0_35
	s_lshl_b32 s2, s47, 6
	s_cmpk_gt_u32 s47, 0xf7
	s_cbranch_scc0 .LBB0_32
	s_lshl_b32 s0, s47, 5
	s_addk_i32 s0, 0x100
	s_and_b32 s1, s2, 64
	s_and_b32 s0, s0, 0x1fc0
	v_readlane_b32 s4, v248, 58
	v_readlane_b32 s5, v248, 59
	s_lshl_b32 s4, s0, 2
	v_or_b32_e32 v0, s1, v129
	v_lshl_add_u64 v[52:53], v[2:3], 0, s[4:5]
	v_lshlrev_b32_e32 v0, 12, v0
	v_lshl_add_u64 v[54:55], v[52:53], 0, v[0:1]
	s_barrier
	global_load_dword v60, v[54:55], off
	s_lshl_b32 s4, s1, 1
	v_or_b32_e32 v0, s1, v91
	v_lshlrev_b32_e32 v0, 12, v0
	v_lshl_add_u64 v[54:55], v[52:53], 0, v[0:1]
	global_load_dword v61, v[54:55], off
	v_or_b32_e32 v0, s1, v92
	v_lshlrev_b32_e32 v0, 12, v0
	v_lshl_add_u64 v[54:55], v[52:53], 0, v[0:1]
	global_load_dword v62, v[54:55], off
	v_or_b32_e32 v0, s1, v93
	v_lshlrev_b32_e32 v0, 12, v0
	v_lshl_add_u64 v[54:55], v[52:53], 0, v[0:1]
	global_load_dword v63, v[54:55], off
	v_or_b32_e32 v0, s1, v94
	v_lshlrev_b32_e32 v0, 12, v0
	v_lshl_add_u64 v[54:55], v[52:53], 0, v[0:1]
	global_load_dword v64, v[54:55], off
	v_or_b32_e32 v0, s1, v95
	v_lshlrev_b32_e32 v0, 12, v0
	v_lshl_add_u64 v[54:55], v[52:53], 0, v[0:1]
	global_load_dword v65, v[54:55], off
	v_or_b32_e32 v0, s1, v96
	v_lshlrev_b32_e32 v0, 12, v0
	v_lshl_add_u64 v[54:55], v[52:53], 0, v[0:1]
	global_load_dword v66, v[54:55], off
	v_or_b32_e32 v0, s1, v97
	v_lshlrev_b32_e32 v0, 12, v0
	v_lshl_add_u64 v[54:55], v[52:53], 0, v[0:1]
	global_load_dword v67, v[54:55], off
	v_or_b32_e32 v0, s1, v98
	v_lshlrev_b32_e32 v0, 12, v0
	v_lshl_add_u64 v[54:55], v[52:53], 0, v[0:1]
	global_load_dword v68, v[54:55], off
	v_or_b32_e32 v0, s1, v99
	v_lshlrev_b32_e32 v0, 12, v0
	v_lshl_add_u64 v[54:55], v[52:53], 0, v[0:1]
	global_load_dword v69, v[54:55], off
	v_or_b32_e32 v0, s1, v100
	v_lshlrev_b32_e32 v0, 12, v0
	v_lshl_add_u64 v[54:55], v[52:53], 0, v[0:1]
	global_load_dword v70, v[54:55], off
	v_or_b32_e32 v0, s1, v101
	v_lshlrev_b32_e32 v0, 12, v0
	v_lshl_add_u64 v[54:55], v[52:53], 0, v[0:1]
	global_load_dword v71, v[54:55], off
	v_or_b32_e32 v0, s1, v102
	v_lshlrev_b32_e32 v0, 12, v0
	v_lshl_add_u64 v[54:55], v[52:53], 0, v[0:1]
	global_load_dword v72, v[54:55], off
	v_add_lshl_u32 v0, s1, v103, 12
	v_lshl_add_u64 v[54:55], v[52:53], 0, v[0:1]
	global_load_dword v73, v[54:55], off
	v_add_lshl_u32 v0, s1, v104, 12
	v_lshl_add_u64 v[54:55], v[52:53], 0, v[0:1]
	global_load_dword v74, v[54:55], off
	v_add_lshl_u32 v0, s1, v105, 12
	v_lshl_add_u64 v[52:53], v[52:53], 0, v[0:1]
	global_load_dword v75, v[52:53], off
	s_mov_b32 s1, s5
	v_writelane_b32 v248, s0, 58
	v_lshl_add_u64 v[52:53], v[4:5], 0, s[4:5]
	s_waitcnt vmcnt(0)
	ds_write_b32 v90, v60
	ds_write_b32 v90, v61 offset:1040
	ds_write_b32 v90, v62 offset:2080
	ds_write_b32 v90, v63 offset:3120
	ds_write_b32 v90, v64 offset:4160
	ds_write_b32 v90, v65 offset:5200
	ds_write_b32 v90, v66 offset:6240
	ds_write_b32 v90, v67 offset:7280
	ds_write_b32 v90, v68 offset:8320
	ds_write_b32 v90, v69 offset:9360
	ds_write_b32 v90, v70 offset:10400
	ds_write_b32 v90, v71 offset:11440
	ds_write_b32 v90, v72 offset:12480
	ds_write_b32 v90, v73 offset:13520
	ds_write_b32 v90, v74 offset:14560
	ds_write_b32 v90, v75 offset:15600
	s_waitcnt lgkmcnt(0)
	s_barrier
	ds_read2_b32 v[54:55], v106 offset1:4
	ds_read2_b32 v[56:57], v106 offset0:8 offset1:12
	v_writelane_b32 v248, s1, 59
	s_movk_i32 s1, 0x7fff
	s_waitcnt lgkmcnt(1)
	v_bfe_u32 v0, v54, 16, 1
	v_add3_u32 v19, v54, v0, s1
	v_or_b32_e32 v0, s0, v129
	v_lshlrev_b32_e32 v0, 8, v0
	v_lshl_add_u64 v[58:59], v[52:53], 0, v[0:1]
	v_bfe_u32 v0, v55, 16, 1
	global_store_short_d16_hi v[58:59], v19, off
	v_add3_u32 v19, v55, v0, s1
	v_or_b32_e32 v0, s0, v91
	v_lshlrev_b32_e32 v0, 8, v0
	v_lshl_add_u64 v[54:55], v[52:53], 0, v[0:1]
	s_waitcnt lgkmcnt(0)
	v_bfe_u32 v0, v56, 16, 1
	global_store_short_d16_hi v[54:55], v19, off
	v_add3_u32 v19, v56, v0, s1
	v_or_b32_e32 v0, s0, v92
	v_lshlrev_b32_e32 v0, 8, v0
	v_lshl_add_u64 v[54:55], v[52:53], 0, v[0:1]
	v_bfe_u32 v0, v57, 16, 1
	global_store_short_d16_hi v[54:55], v19, off
	v_add3_u32 v19, v57, v0, s1
	v_or_b32_e32 v0, s0, v93
	v_lshlrev_b32_e32 v0, 8, v0
	v_lshl_add_u64 v[54:55], v[52:53], 0, v[0:1]
	global_store_short_d16_hi v[54:55], v19, off
	ds_read2_b32 v[54:55], v106 offset0:16 offset1:20
	s_waitcnt lgkmcnt(0)
	v_bfe_u32 v0, v54, 16, 1
	v_add3_u32 v19, v54, v0, s1
	v_or_b32_e32 v0, s0, v94
	v_lshlrev_b32_e32 v0, 8, v0
	v_lshl_add_u64 v[56:57], v[52:53], 0, v[0:1]
	v_bfe_u32 v0, v55, 16, 1
	global_store_short_d16_hi v[56:57], v19, off
	v_add3_u32 v19, v55, v0, s1
	v_or_b32_e32 v0, s0, v95
	v_lshlrev_b32_e32 v0, 8, v0
	v_lshl_add_u64 v[54:55], v[52:53], 0, v[0:1]
	global_store_short_d16_hi v[54:55], v19, off
	ds_read2_b32 v[54:55], v106 offset0:24 offset1:28
	s_waitcnt lgkmcnt(0)
	v_bfe_u32 v0, v54, 16, 1
	v_add3_u32 v19, v54, v0, s1
	v_or_b32_e32 v0, s0, v96
	v_lshlrev_b32_e32 v0, 8, v0
	v_lshl_add_u64 v[56:57], v[52:53], 0, v[0:1]
	v_bfe_u32 v0, v55, 16, 1
	global_store_short_d16_hi v[56:57], v19, off
	v_add3_u32 v19, v55, v0, s1
	v_or_b32_e32 v0, s0, v97
	v_lshlrev_b32_e32 v0, 8, v0
	v_lshl_add_u64 v[54:55], v[52:53], 0, v[0:1]
	global_store_short_d16_hi v[54:55], v19, off
	ds_read2_b32 v[54:55], v106 offset0:32 offset1:36
	s_waitcnt lgkmcnt(0)
	v_bfe_u32 v0, v54, 16, 1
	v_add3_u32 v19, v54, v0, s1
	v_or_b32_e32 v0, s0, v98
	v_lshlrev_b32_e32 v0, 8, v0
	v_lshl_add_u64 v[56:57], v[52:53], 0, v[0:1]
	v_bfe_u32 v0, v55, 16, 1
	global_store_short_d16_hi v[56:57], v19, off
	v_add3_u32 v19, v55, v0, s1
	v_or_b32_e32 v0, s0, v99
	v_lshlrev_b32_e32 v0, 8, v0
	v_lshl_add_u64 v[54:55], v[52:53], 0, v[0:1]
	global_store_short_d16_hi v[54:55], v19, off
	ds_read2_b32 v[54:55], v106 offset0:40 offset1:44
	s_waitcnt lgkmcnt(0)
	v_bfe_u32 v0, v54, 16, 1
	v_add3_u32 v19, v54, v0, s1
	v_or_b32_e32 v0, s0, v100
	v_lshlrev_b32_e32 v0, 8, v0
	v_lshl_add_u64 v[56:57], v[52:53], 0, v[0:1]
	v_bfe_u32 v0, v55, 16, 1
	global_store_short_d16_hi v[56:57], v19, off
	v_add3_u32 v19, v55, v0, s1
	v_or_b32_e32 v0, s0, v101
	v_lshlrev_b32_e32 v0, 8, v0
	v_lshl_add_u64 v[54:55], v[52:53], 0, v[0:1]
	global_store_short_d16_hi v[54:55], v19, off
	ds_read2_b32 v[54:55], v106 offset0:48 offset1:52
	s_waitcnt lgkmcnt(0)
	v_bfe_u32 v0, v54, 16, 1
	v_add3_u32 v19, v54, v0, s1
	v_or_b32_e32 v0, s0, v102
	v_lshlrev_b32_e32 v0, 8, v0
	v_lshl_add_u64 v[56:57], v[52:53], 0, v[0:1]
	v_bfe_u32 v0, v55, 16, 1
	global_store_short_d16_hi v[56:57], v19, off
	v_add3_u32 v19, v55, v0, s1
	v_add_lshl_u32 v0, s0, v103, 8
	v_lshl_add_u64 v[54:55], v[52:53], 0, v[0:1]
	global_store_short_d16_hi v[54:55], v19, off
	ds_read2_b32 v[54:55], v106 offset0:56 offset1:60
	s_waitcnt lgkmcnt(0)
	v_bfe_u32 v0, v54, 16, 1
	v_add3_u32 v19, v54, v0, s1
	v_add_lshl_u32 v0, s0, v104, 8
	v_lshl_add_u64 v[56:57], v[52:53], 0, v[0:1]
	v_bfe_u32 v0, v55, 16, 1
	global_store_short_d16_hi v[56:57], v19, off
	v_add3_u32 v19, v55, v0, s1
	v_add_lshl_u32 v0, s0, v105, 8
	v_lshl_add_u64 v[52:53], v[52:53], 0, v[0:1]
	global_store_short_d16_hi v[52:53], v19, off
	s_mov_b64 s[0:1], 0
.LBB0_32:
	s_andn2_b64 vcc, exec, s[0:1]
	s_cbranch_vccnz .LBB0_34
	v_readlane_b32 s0, v248, 58
	v_readlane_b32 s1, v248, 59
	s_add_i32 s0, s2, 0xffffc600
	v_mov_b32_e32 v21, v1
	v_lshl_add_u64 v[52:53], s[0:1], 2, v[6:7]
	v_lshl_add_u64 v[54:55], v[52:53], 0, v[20:21]
	s_barrier
	global_load_dword v60, v[54:55], off
	v_mov_b32_e32 v23, v1
	v_lshl_add_u64 v[54:55], v[52:53], 0, v[22:23]
	v_mov_b32_e32 v25, v1
	v_mov_b32_e32 v27, v1
	v_mov_b32_e32 v29, v1
	v_mov_b32_e32 v31, v1
	v_mov_b32_e32 v33, v1
	v_mov_b32_e32 v35, v1
	v_mov_b32_e32 v37, v1
	v_mov_b32_e32 v39, v1
	v_mov_b32_e32 v41, v1
	v_mov_b32_e32 v43, v1
	v_mov_b32_e32 v45, v1
	v_mov_b32_e32 v47, v1
	v_mov_b32_e32 v49, v1
	v_mov_b32_e32 v51, v1
	s_movk_i32 s2, 0x7fff
	global_load_dword v61, v[54:55], off
	v_lshl_add_u64 v[54:55], v[52:53], 0, v[24:25]
	global_load_dword v62, v[54:55], off
	v_lshl_add_u64 v[54:55], v[52:53], 0, v[26:27]
	global_load_dword v63, v[54:55], off
	v_lshl_add_u64 v[54:55], v[52:53], 0, v[28:29]
	global_load_dword v64, v[54:55], off
	v_lshl_add_u64 v[54:55], v[52:53], 0, v[30:31]
	global_load_dword v65, v[54:55], off
	v_lshl_add_u64 v[54:55], v[52:53], 0, v[32:33]
	global_load_dword v66, v[54:55], off
	v_lshl_add_u64 v[54:55], v[52:53], 0, v[34:35]
	global_load_dword v67, v[54:55], off
	v_lshl_add_u64 v[54:55], v[52:53], 0, v[36:37]
	global_load_dword v68, v[54:55], off
	v_lshl_add_u64 v[54:55], v[52:53], 0, v[38:39]
	global_load_dword v69, v[54:55], off
	v_lshl_add_u64 v[54:55], v[52:53], 0, v[40:41]
	global_load_dword v70, v[54:55], off
	v_lshl_add_u64 v[54:55], v[52:53], 0, v[42:43]
	global_load_dword v71, v[54:55], off
	v_lshl_add_u64 v[54:55], v[52:53], 0, v[44:45]
	global_load_dword v72, v[54:55], off
	v_lshl_add_u64 v[54:55], v[52:53], 0, v[46:47]
	global_load_dword v73, v[54:55], off
	v_lshl_add_u64 v[54:55], v[52:53], 0, v[48:49]
	v_lshl_add_u64 v[52:53], v[52:53], 0, v[50:51]
	global_load_dword v74, v[54:55], off
	global_load_dword v75, v[52:53], off
	s_waitcnt vmcnt(0)
	ds_write_b32 v90, v60
	ds_write_b32 v90, v61 offset:1040
	ds_write_b32 v90, v62 offset:2080
	ds_write_b32 v90, v63 offset:3120
	ds_write_b32 v90, v64 offset:4160
	ds_write_b32 v90, v65 offset:5200
	ds_write_b32 v90, v66 offset:6240
	ds_write_b32 v90, v67 offset:7280
	ds_write_b32 v90, v68 offset:8320
	ds_write_b32 v90, v69 offset:9360
	ds_write_b32 v90, v70 offset:10400
	ds_write_b32 v90, v71 offset:11440
	ds_write_b32 v90, v72 offset:12480
	ds_write_b32 v90, v73 offset:13520
	ds_write_b32 v90, v74 offset:14560
	ds_write_b32 v90, v75 offset:15600
	s_waitcnt lgkmcnt(0)
	s_barrier
	ds_read2_b32 v[52:53], v106 offset1:4
	ds_read2_b32 v[54:55], v106 offset0:8 offset1:12
	s_waitcnt lgkmcnt(1)
	v_bfe_u32 v0, v52, 16, 1
	v_add3_u32 v19, v52, v0, s2
	v_or_b32_e32 v0, s0, v129
	v_lshlrev_b64 v[56:57], 7, v[0:1]
	v_lshl_add_u64 v[56:57], v[10:11], 0, v[56:57]
	v_bfe_u32 v0, v53, 16, 1
	global_store_short_d16_hi v[56:57], v19, off
	v_add3_u32 v19, v53, v0, s2
	v_or_b32_e32 v0, s0, v91
	v_lshlrev_b64 v[52:53], 7, v[0:1]
	v_lshl_add_u64 v[52:53], v[10:11], 0, v[52:53]
	s_waitcnt lgkmcnt(0)
	v_bfe_u32 v0, v54, 16, 1
	global_store_short_d16_hi v[52:53], v19, off
	v_add3_u32 v19, v54, v0, s2
	v_or_b32_e32 v0, s0, v92
	v_lshlrev_b64 v[52:53], 7, v[0:1]
	v_lshl_add_u64 v[52:53], v[10:11], 0, v[52:53]
	v_bfe_u32 v0, v55, 16, 1
	global_store_short_d16_hi v[52:53], v19, off
	v_add3_u32 v19, v55, v0, s2
	v_or_b32_e32 v0, s0, v93
	v_lshlrev_b64 v[52:53], 7, v[0:1]
	v_lshl_add_u64 v[52:53], v[10:11], 0, v[52:53]
	global_store_short_d16_hi v[52:53], v19, off
	ds_read2_b32 v[52:53], v106 offset0:16 offset1:20
	s_waitcnt lgkmcnt(0)
	v_bfe_u32 v0, v52, 16, 1
	v_add3_u32 v19, v52, v0, s2
	v_or_b32_e32 v0, s0, v94
	v_lshlrev_b64 v[54:55], 7, v[0:1]
	v_lshl_add_u64 v[54:55], v[10:11], 0, v[54:55]
	v_bfe_u32 v0, v53, 16, 1
	global_store_short_d16_hi v[54:55], v19, off
	v_add3_u32 v19, v53, v0, s2
	v_or_b32_e32 v0, s0, v95
	v_lshlrev_b64 v[52:53], 7, v[0:1]
	v_lshl_add_u64 v[52:53], v[10:11], 0, v[52:53]
	global_store_short_d16_hi v[52:53], v19, off
	ds_read2_b32 v[52:53], v106 offset0:24 offset1:28
	s_waitcnt lgkmcnt(0)
	v_bfe_u32 v0, v52, 16, 1
	v_add3_u32 v19, v52, v0, s2
	v_or_b32_e32 v0, s0, v96
	v_lshlrev_b64 v[54:55], 7, v[0:1]
	v_lshl_add_u64 v[54:55], v[10:11], 0, v[54:55]
	v_bfe_u32 v0, v53, 16, 1
	global_store_short_d16_hi v[54:55], v19, off
	v_add3_u32 v19, v53, v0, s2
	v_or_b32_e32 v0, s0, v97
	v_lshlrev_b64 v[52:53], 7, v[0:1]
	v_lshl_add_u64 v[52:53], v[10:11], 0, v[52:53]
	global_store_short_d16_hi v[52:53], v19, off
	ds_read2_b32 v[52:53], v106 offset0:32 offset1:36
	s_waitcnt lgkmcnt(0)
	v_bfe_u32 v0, v52, 16, 1
	v_add3_u32 v19, v52, v0, s2
	v_or_b32_e32 v0, s0, v98
	v_lshlrev_b64 v[54:55], 7, v[0:1]
	v_lshl_add_u64 v[54:55], v[10:11], 0, v[54:55]
	v_bfe_u32 v0, v53, 16, 1
	global_store_short_d16_hi v[54:55], v19, off
	v_add3_u32 v19, v53, v0, s2
	v_or_b32_e32 v0, s0, v99
	v_lshlrev_b64 v[52:53], 7, v[0:1]
	v_lshl_add_u64 v[52:53], v[10:11], 0, v[52:53]
	global_store_short_d16_hi v[52:53], v19, off
	ds_read2_b32 v[52:53], v106 offset0:40 offset1:44
	s_waitcnt lgkmcnt(0)
	v_bfe_u32 v0, v52, 16, 1
	v_add3_u32 v19, v52, v0, s2
	v_or_b32_e32 v0, s0, v100
	v_lshlrev_b64 v[54:55], 7, v[0:1]
	v_lshl_add_u64 v[54:55], v[10:11], 0, v[54:55]
	v_bfe_u32 v0, v53, 16, 1
	global_store_short_d16_hi v[54:55], v19, off
	v_add3_u32 v19, v53, v0, s2
	v_or_b32_e32 v0, s0, v101
	v_lshlrev_b64 v[52:53], 7, v[0:1]
	v_lshl_add_u64 v[52:53], v[10:11], 0, v[52:53]
	global_store_short_d16_hi v[52:53], v19, off
	ds_read2_b32 v[52:53], v106 offset0:48 offset1:52
	s_waitcnt lgkmcnt(0)
	v_bfe_u32 v0, v52, 16, 1
	v_add3_u32 v19, v52, v0, s2
	v_or_b32_e32 v0, s0, v102
	v_lshlrev_b64 v[54:55], 7, v[0:1]
	v_lshl_add_u64 v[54:55], v[10:11], 0, v[54:55]
	v_bfe_u32 v0, v53, 16, 1
	global_store_short_d16_hi v[54:55], v19, off
	v_add3_u32 v19, v53, v0, s2
	v_add_u32_e32 v0, s0, v103
	v_lshlrev_b64 v[52:53], 7, v[0:1]
	v_lshl_add_u64 v[52:53], v[10:11], 0, v[52:53]
	global_store_short_d16_hi v[52:53], v19, off
	ds_read2_b32 v[52:53], v106 offset0:56 offset1:60
	s_waitcnt lgkmcnt(0)
	v_bfe_u32 v0, v52, 16, 1
	v_add3_u32 v19, v52, v0, s2
	v_add_u32_e32 v0, s0, v104
	v_lshlrev_b64 v[54:55], 7, v[0:1]
	v_lshl_add_u64 v[54:55], v[10:11], 0, v[54:55]
	v_bfe_u32 v0, v53, 16, 1
	global_store_short_d16_hi v[54:55], v19, off
	v_add3_u32 v19, v53, v0, s2
	v_writelane_b32 v248, s0, 58
	s_nop 1
	v_add_u32_e32 v0, s0, v105
	v_lshlrev_b64 v[52:53], 7, v[0:1]
	v_lshl_add_u64 v[52:53], v[10:11], 0, v[52:53]
	v_writelane_b32 v248, s1, 59
	global_store_short_d16_hi v[52:53], v19, off

.LBB0_35:
	s_andn2_b64 vcc, exec, s[0:1]
	s_cbranch_vccnz .LBB0_37
	v_readlane_b32 s2, v248, 58
	s_lshl_b32 s0, s47, 6
	v_readlane_b32 s3, v248, 59
	s_mov_b32 s1, s3
	s_addk_i32 s0, 0xca00
	v_lshl_add_u64 v[52:53], s[0:1], 2, v[8:9]
	v_mov_b32_e32 v21, v1
	v_lshl_add_u64 v[54:55], v[52:53], 0, v[20:21]
	s_barrier
	global_load_dword v60, v[54:55], off
	v_mov_b32_e32 v23, v1
	v_lshl_add_u64 v[54:55], v[52:53], 0, v[22:23]
	v_mov_b32_e32 v25, v1
	v_mov_b32_e32 v27, v1
	v_mov_b32_e32 v29, v1
	v_mov_b32_e32 v31, v1
	v_mov_b32_e32 v33, v1
	v_mov_b32_e32 v35, v1
	v_mov_b32_e32 v37, v1
	v_mov_b32_e32 v39, v1
	v_mov_b32_e32 v41, v1
	v_mov_b32_e32 v43, v1
	v_mov_b32_e32 v45, v1
	v_mov_b32_e32 v47, v1
	v_mov_b32_e32 v49, v1
	v_mov_b32_e32 v51, v1
	s_movk_i32 s2, 0x7fff
	global_load_dword v61, v[54:55], off
	v_lshl_add_u64 v[54:55], v[52:53], 0, v[24:25]
	global_load_dword v62, v[54:55], off
	v_lshl_add_u64 v[54:55], v[52:53], 0, v[26:27]
	global_load_dword v63, v[54:55], off
	v_lshl_add_u64 v[54:55], v[52:53], 0, v[28:29]
	global_load_dword v64, v[54:55], off
	v_lshl_add_u64 v[54:55], v[52:53], 0, v[30:31]
	global_load_dword v65, v[54:55], off
	v_lshl_add_u64 v[54:55], v[52:53], 0, v[32:33]
	global_load_dword v66, v[54:55], off
	v_lshl_add_u64 v[54:55], v[52:53], 0, v[34:35]
	global_load_dword v67, v[54:55], off
	v_lshl_add_u64 v[54:55], v[52:53], 0, v[36:37]
	global_load_dword v68, v[54:55], off
	v_lshl_add_u64 v[54:55], v[52:53], 0, v[38:39]
	global_load_dword v69, v[54:55], off
	v_lshl_add_u64 v[54:55], v[52:53], 0, v[40:41]
	global_load_dword v70, v[54:55], off
	v_lshl_add_u64 v[54:55], v[52:53], 0, v[42:43]
	global_load_dword v71, v[54:55], off
	v_lshl_add_u64 v[54:55], v[52:53], 0, v[44:45]
	global_load_dword v72, v[54:55], off
	v_lshl_add_u64 v[54:55], v[52:53], 0, v[46:47]
	global_load_dword v73, v[54:55], off
	v_lshl_add_u64 v[54:55], v[52:53], 0, v[48:49]
	v_lshl_add_u64 v[52:53], v[52:53], 0, v[50:51]
	global_load_dword v74, v[54:55], off
	global_load_dword v75, v[52:53], off
	s_waitcnt vmcnt(0)
	ds_write_b32 v90, v60
	ds_write_b32 v90, v61 offset:1040
	ds_write_b32 v90, v62 offset:2080
	ds_write_b32 v90, v63 offset:3120
	ds_write_b32 v90, v64 offset:4160
	ds_write_b32 v90, v65 offset:5200
	ds_write_b32 v90, v66 offset:6240
	ds_write_b32 v90, v67 offset:7280
	ds_write_b32 v90, v68 offset:8320
	ds_write_b32 v90, v69 offset:9360
	ds_write_b32 v90, v70 offset:10400
	ds_write_b32 v90, v71 offset:11440
	ds_write_b32 v90, v72 offset:12480
	ds_write_b32 v90, v73 offset:13520
	ds_write_b32 v90, v74 offset:14560
	ds_write_b32 v90, v75 offset:15600
	s_waitcnt lgkmcnt(0)
	s_barrier
	ds_read2_b32 v[52:53], v106 offset1:4
	ds_read2_b32 v[54:55], v106 offset0:8 offset1:12
	s_waitcnt lgkmcnt(1)
	v_bfe_u32 v0, v52, 16, 1
	v_add3_u32 v19, v52, v0, s2
	v_or_b32_e32 v0, s0, v129
	v_lshlrev_b64 v[56:57], 7, v[0:1]
	v_lshl_add_u64 v[56:57], v[12:13], 0, v[56:57]
	v_bfe_u32 v0, v53, 16, 1
	global_store_short_d16_hi v[56:57], v19, off
	v_add3_u32 v19, v53, v0, s2
	v_or_b32_e32 v0, s0, v91
	v_lshlrev_b64 v[52:53], 7, v[0:1]
	v_lshl_add_u64 v[52:53], v[12:13], 0, v[52:53]
	s_waitcnt lgkmcnt(0)
	v_bfe_u32 v0, v54, 16, 1
	global_store_short_d16_hi v[52:53], v19, off
	v_add3_u32 v19, v54, v0, s2
	v_or_b32_e32 v0, s0, v92
	v_lshlrev_b64 v[52:53], 7, v[0:1]
	v_lshl_add_u64 v[52:53], v[12:13], 0, v[52:53]
	v_bfe_u32 v0, v55, 16, 1
	global_store_short_d16_hi v[52:53], v19, off
	v_add3_u32 v19, v55, v0, s2
	v_or_b32_e32 v0, s0, v93
	v_lshlrev_b64 v[52:53], 7, v[0:1]
	v_lshl_add_u64 v[52:53], v[12:13], 0, v[52:53]
	global_store_short_d16_hi v[52:53], v19, off
	ds_read2_b32 v[52:53], v106 offset0:16 offset1:20
	s_waitcnt lgkmcnt(0)
	v_bfe_u32 v0, v52, 16, 1
	v_add3_u32 v19, v52, v0, s2
	v_or_b32_e32 v0, s0, v94
	v_lshlrev_b64 v[54:55], 7, v[0:1]
	v_lshl_add_u64 v[54:55], v[12:13], 0, v[54:55]
	v_bfe_u32 v0, v53, 16, 1
	global_store_short_d16_hi v[54:55], v19, off
	v_add3_u32 v19, v53, v0, s2
	v_or_b32_e32 v0, s0, v95
	v_lshlrev_b64 v[52:53], 7, v[0:1]
	v_lshl_add_u64 v[52:53], v[12:13], 0, v[52:53]
	global_store_short_d16_hi v[52:53], v19, off
	ds_read2_b32 v[52:53], v106 offset0:24 offset1:28
	s_waitcnt lgkmcnt(0)
	v_bfe_u32 v0, v52, 16, 1
	v_add3_u32 v19, v52, v0, s2
	v_or_b32_e32 v0, s0, v96
	v_lshlrev_b64 v[54:55], 7, v[0:1]
	v_lshl_add_u64 v[54:55], v[12:13], 0, v[54:55]
	v_bfe_u32 v0, v53, 16, 1
	global_store_short_d16_hi v[54:55], v19, off
	v_add3_u32 v19, v53, v0, s2
	v_or_b32_e32 v0, s0, v97
	v_lshlrev_b64 v[52:53], 7, v[0:1]
	v_lshl_add_u64 v[52:53], v[12:13], 0, v[52:53]
	global_store_short_d16_hi v[52:53], v19, off
	ds_read2_b32 v[52:53], v106 offset0:32 offset1:36
	s_waitcnt lgkmcnt(0)
	v_bfe_u32 v0, v52, 16, 1
	v_add3_u32 v19, v52, v0, s2
	v_or_b32_e32 v0, s0, v98
	v_lshlrev_b64 v[54:55], 7, v[0:1]
	v_lshl_add_u64 v[54:55], v[12:13], 0, v[54:55]
	v_bfe_u32 v0, v53, 16, 1
	global_store_short_d16_hi v[54:55], v19, off
	v_add3_u32 v19, v53, v0, s2
	v_or_b32_e32 v0, s0, v99
	v_lshlrev_b64 v[52:53], 7, v[0:1]
	v_lshl_add_u64 v[52:53], v[12:13], 0, v[52:53]
	global_store_short_d16_hi v[52:53], v19, off
	ds_read2_b32 v[52:53], v106 offset0:40 offset1:44
	s_waitcnt lgkmcnt(0)
	v_bfe_u32 v0, v52, 16, 1
	v_add3_u32 v19, v52, v0, s2
	v_or_b32_e32 v0, s0, v100
	v_lshlrev_b64 v[54:55], 7, v[0:1]
	v_lshl_add_u64 v[54:55], v[12:13], 0, v[54:55]
	v_bfe_u32 v0, v53, 16, 1
	global_store_short_d16_hi v[54:55], v19, off
	v_add3_u32 v19, v53, v0, s2
	v_or_b32_e32 v0, s0, v101
	v_lshlrev_b64 v[52:53], 7, v[0:1]
	v_lshl_add_u64 v[52:53], v[12:13], 0, v[52:53]
	global_store_short_d16_hi v[52:53], v19, off
	ds_read2_b32 v[52:53], v106 offset0:48 offset1:52
	s_waitcnt lgkmcnt(0)
	v_bfe_u32 v0, v52, 16, 1
	v_add3_u32 v19, v52, v0, s2
	v_or_b32_e32 v0, s0, v102
	v_lshlrev_b64 v[54:55], 7, v[0:1]
	v_lshl_add_u64 v[54:55], v[12:13], 0, v[54:55]
	v_bfe_u32 v0, v53, 16, 1
	global_store_short_d16_hi v[54:55], v19, off
	v_add3_u32 v19, v53, v0, s2
	v_add_u32_e32 v0, s0, v103
	v_lshlrev_b64 v[52:53], 7, v[0:1]
	v_lshl_add_u64 v[52:53], v[12:13], 0, v[52:53]
	global_store_short_d16_hi v[52:53], v19, off
	ds_read2_b32 v[52:53], v106 offset0:56 offset1:60
	s_waitcnt lgkmcnt(0)
	v_bfe_u32 v0, v52, 16, 1
	v_add3_u32 v19, v52, v0, s2
	v_add_u32_e32 v0, s0, v104
	v_lshlrev_b64 v[54:55], 7, v[0:1]
	v_lshl_add_u64 v[54:55], v[12:13], 0, v[54:55]
	v_bfe_u32 v0, v53, 16, 1
	global_store_short_d16_hi v[54:55], v19, off
	v_add3_u32 v19, v53, v0, s2
	v_writelane_b32 v248, s0, 58
	s_nop 1
	v_add_u32_e32 v0, s0, v105
	v_lshlrev_b64 v[52:53], 7, v[0:1]
	v_lshl_add_u64 v[52:53], v[12:13], 0, v[52:53]
	v_writelane_b32 v248, s1, 59
	global_store_short_d16_hi v[52:53], v19, off
